# fix: MLA rare rescale path used registers now holding live exp results; remapped its temporaries (verified by forcing the rescale threshold to 0)
# baseline (speedup 1.0000x reference)
; #define SBAR() __builtin_amdgcn_sched_barrier(0)
; #define SLOAD(i, k0) do { sr_[i].vs0 = *reinterpret_cast<const bf16x8*>(vptr + (size_t)((k0) + sr) * vstr); \
;     sr_[i].vs1 = *reinterpret_cast<const bf16x8*>(vptr + (size_t)((k0) + 32 + sr) * vstr); \
;     sr_[i].ks0 = *reinterpret_cast<const bf16x8*>(kptr + (size_t)((k0) + sr) * kstr); \
;     sr_[i].ks1 = *reinterpret_cast<const bf16x8*>(kptr + (size_t)((k0) + 32 + sr) * kstr); } while (0)
; #define SWRITE(b, i) do { *(LAS bf16x8*)(V_lds + (b) * SHM_V + vst0) = sr_[i].vs0;          \
;     *(LAS bf16x8*)(V_lds + (b) * SHM_V + vst1) = sr_[i].vs1; const int kc = sc * 2;               \
;     *(LAS bf16x8*)(K_lds + (b) * SHM_K + KSWZ(sr, kc)) = sr_[i].ks0;                       \
;     *(LAS bf16x8*)(K_lds + (b) * SHM_K + KSWZ(32 + sr, kc)) = sr_[i].ks1; } while (0)
; #define SWAIT() asm volatile("s_waitcnt vmcnt(4)" ::: "memory")
; template <int NDQ, int NDV> ...
;     ...
;     SBAR(); qkt<NDQ>(pB0, pB1, K_lds + SHM_K, qr, r32, hi);
;     finishSM(pA0, pA1, alA, l_reg, pa0, pa1, pa2, pa3); SBAR();
;     SLOAD(SO, (j + 2) * 64); SBAR();
;     pv_d0<NDV>(o, vb0, pa0, pa1, pa2, pa3); partialSM(pB0, pB1, m_reg, mnB, alB, Cs, thr);
;     ...
;     __syncthreads(); SWAIT(); SWRITE(1, SO);
.LBB0_1488:
	ds_read_b128 v[32:35], v175 offset:49152
	ds_read_b128 v[36:39], v175 offset:57344
	ds_read_b128 v[192:195], v176 offset:49152
	ds_read_b128 v[196:199], v176 offset:57344
	ds_read_b128 v[200:203], v177 offset:49152
	ds_read_b128 v[204:207], v177 offset:57344
	ds_read_b128 v[208:211], v178 offset:49152
	ds_read_b128 v[212:215], v178 offset:57344
	ds_read_b128 v[216:219], v179 offset:49152
	ds_read_b128 v[220:223], v179 offset:57344
	v_add_f32_e32 v121, 0, v130
	v_add_f32_e32 v121, v134, v121
	s_waitcnt lgkmcnt(9)
	v_mfma_f32_32x32x16_bf16 v[48:63], v[32:35], v[84:87], 0
	v_add_f32_e32 v121, v131, v121
	v_add_f32_e32 v121, v135, v121
	v_add_f32_e32 v121, v132, v121
	v_add_f32_e32 v121, v185, v121
	v_add_f32_e32 v121, v133, v121
	v_add_f32_e32 v121, v186, v121
	v_add_f32_e32 v121, v122, v121
	v_add_f32_e32 v121, v125, v121
	s_waitcnt lgkmcnt(8)
	v_mfma_f32_32x32x16_bf16 v[32:47], v[36:39], v[84:87], 0
	v_add_f32_e32 v121, v123, v121
	v_add_f32_e32 v121, v126, v121
	v_exp_f32_e32 v116, v116
	v_add_f32_e32 v121, v124, v121
	v_exp_f32_e32 v117, v117
	v_add_f32_e32 v121, v127, v121
	s_waitcnt lgkmcnt(7)
	v_mfma_f32_32x32x16_bf16 v[48:63], v[192:195], v[80:83], v[48:63]
	v_exp_f32_e32 v114, v114
	v_add_f32_e32 v121, v128, v121
	v_exp_f32_e32 v115, v115
	v_add_f32_e32 v121, v129, v121
	v_exp_f32_e32 v110, v110
	s_waitcnt lgkmcnt(6)
	v_mfma_f32_32x32x16_bf16 v[32:47], v[196:199], v[80:83], v[32:47]
	v_add_f32_e32 v121, v116, v121
	v_exp_f32_e32 v111, v111
	v_add_f32_e32 v121, v117, v121
	v_exp_f32_e32 v106, v106
	v_add_f32_e32 v121, v114, v121
	s_waitcnt lgkmcnt(5)
	v_mfma_f32_32x32x16_bf16 v[48:63], v[200:203], v[76:79], v[48:63]
	ds_read_b128 v[224:227], v180 offset:49152
	ds_read_b128 v[228:231], v180 offset:57344
	v_exp_f32_e32 v107, v107
	v_add_f32_e32 v121, v115, v121
	v_exp_f32_e32 v104, v104
	v_add_f32_e32 v121, v110, v121
	v_exp_f32_e32 v105, v105
	s_waitcnt lgkmcnt(6)
	v_mfma_f32_32x32x16_bf16 v[32:47], v[204:207], v[76:79], v[32:47]
	v_add_f32_e32 v121, v111, v121
	v_exp_f32_e32 v118, v118
	v_add_f32_e32 v121, v106, v121
	v_exp_f32_e32 v119, v119
	v_add_f32_e32 v121, v107, v121
	s_waitcnt lgkmcnt(5)
	v_mfma_f32_32x32x16_bf16 v[48:63], v[208:211], v[72:75], v[48:63]
	v_exp_f32_e32 v112, v112
	v_add_f32_e32 v121, v104, v121
	v_exp_f32_e32 v113, v113
	v_add_f32_e32 v121, v105, v121
	v_exp_f32_e32 v108, v108
	s_waitcnt lgkmcnt(4)
	v_mfma_f32_32x32x16_bf16 v[32:47], v[212:215], v[72:75], v[32:47]
	v_add_f32_e32 v121, v118, v121
	v_exp_f32_e32 v109, v109
	v_add_f32_e32 v121, v119, v121
	v_add_f32_e32 v121, v112, v121
	v_add_f32_e32 v121, v113, v121
	v_add_f32_e32 v121, v108, v121
	v_add_f32_e32 v182, v109, v121
	s_waitcnt lgkmcnt(3)
	v_mfma_f32_32x32x16_bf16 v[48:63], v[216:219], v[68:71], v[48:63]
	v_mov_b32_e32 v183, v182
	v_cvt_pk_bf16_f32 v130, v130, v134
	v_cvt_pk_bf16_f32 v131, v131, v135
	v_cvt_pk_bf16_f32 v132, v132, v185
	v_cvt_pk_bf16_f32 v133, v133, v186
	v_cvt_pk_bf16_f32 v122, v122, v125
	v_cvt_pk_bf16_f32 v123, v123, v126
	v_cvt_pk_bf16_f32 v124, v124, v127
	s_waitcnt lgkmcnt(2)
	v_mfma_f32_32x32x16_bf16 v[32:47], v[220:223], v[68:71], v[32:47]
	v_cvt_pk_bf16_f32 v125, v128, v129
	v_cvt_pk_bf16_f32 v126, v116, v117
	v_cvt_pk_bf16_f32 v127, v114, v115
	v_cvt_pk_bf16_f32 v128, v110, v111
	v_cvt_pk_bf16_f32 v129, v106, v107
	v_cvt_pk_bf16_f32 v184, v104, v105
	v_cvt_pk_bf16_f32 v185, v118, v119
	v_cvt_pk_bf16_f32 v186, v112, v113
	s_waitcnt lgkmcnt(1)
	v_mfma_f32_32x32x16_bf16 v[48:63], v[224:227], v[64:67], v[48:63]
	v_permlane32_swap_b32_e32 v182, v183
	v_cvt_pk_bf16_f32 v187, v108, v109
	v_permlane32_swap_b32_e32 v184, v186
	v_permlane32_swap_b32_e32 v130, v132
	v_permlane32_swap_b32_e32 v131, v133
	v_permlane32_swap_b32_e32 v122, v124
	v_permlane32_swap_b32_e32 v123, v125
	v_permlane32_swap_b32_e32 v126, v128
	s_waitcnt lgkmcnt(0)
	v_mfma_f32_32x32x16_bf16 v[32:47], v[228:231], v[64:67], v[32:47]
	v_permlane32_swap_b32_e32 v127, v129
	v_permlane32_swap_b32_e32 v185, v187
	v_add_co_u32_e32 v104, vcc, s48, v154
	v_lshl_add_u64 v[112:113], v[150:151], 0, v[160:161]
	s_nop 0
	v_addc_co_u32_e32 v105, vcc, -1, v155, vcc
	v_add_co_u32_e32 v108, vcc, s49, v154
	v_lshl_add_u64 v[116:117], v[150:151], 0, v[158:159]
	s_nop 0
	v_addc_co_u32_e32 v109, vcc, -1, v155, vcc
	global_load_dwordx4 v[104:107], v[104:105], off
	s_nop 0
	global_load_dwordx4 v[108:111], v[108:109], off
	s_nop 0
	global_load_dwordx4 v[112:115], v[112:113], off
	s_nop 0
	global_load_dwordx4 v[116:119], v[116:117], off
	s_waitcnt vmcnt(4)
	ds_write_b128 v171, v[88:91] offset:32768
	ds_write_b128 v172, v[92:95] offset:32768
	ds_read_b64_tr_b16 v[192:193], v170 offset:0
	ds_read_b64_tr_b16 v[194:195], v170 offset:0x800
	ds_read_b64_tr_b16 v[196:197], v170 offset:0x1000
	ds_read_b64_tr_b16 v[198:199], v170 offset:0x1800
	ds_read_b64_tr_b16 v[200:201], v170 offset:0x2000
	ds_read_b64_tr_b16 v[202:203], v170 offset:0x2800
	ds_read_b64_tr_b16 v[204:205], v170 offset:0x3000
	ds_read_b64_tr_b16 v[206:207], v170 offset:0x3800
	s_waitcnt lgkmcnt(6)
; #define SWRITE(b, i) do { *(LAS bf16x8*)(V_lds + (b) * SHM_V + vst0) = sr_[i].vs0;          \
;     *(LAS bf16x8*)(V_lds + (b) * SHM_V + vst1) = sr_[i].vs1; const int kc = sc * 2;               \
;     *(LAS bf16x8*)(K_lds + (b) * SHM_K + KSWZ(sr, kc)) = sr_[i].ks0;                       \
;     *(LAS bf16x8*)(K_lds + (b) * SHM_K + KSWZ(32 + sr, kc)) = sr_[i].ks1; } while (0)
; #define SWAIT() asm volatile("s_waitcnt vmcnt(4)" ::: "memory")
; #define RESC(a) do { if (__any((a) < 1.f)) { if (hi == 0) al_l[r32] = (a); asm volatile("s_waitcnt lgkmcnt(0)" ::: "memory"); \
;     _Pragma("unroll") for (int d = 0; d < NDV; ++d) _Pragma("unroll") for (int r = 0; r < 16; ++r) o[d][r] *= al_l[crow(r, hi)]; } } while (0)
; template <int NDQ, int NDV> ...
;     ...
;     pv_d0<NDV>(o, vb0, pa0, pa1, pa2, pa3); partialSM(pB0, pB1, m_reg, mnB, alB, Cs, thr);
;     __syncthreads(); SWAIT(); SWRITE(0, SE);
;     RESC(alB); __syncthreads();
	v_mfma_f32_32x32x16_bf16 v[0:15], v[130:133], v[192:195], v[0:15]
	ds_read_b64_tr_b16 v[192:193], v170 offset:0x200
	ds_read_b64_tr_b16 v[194:195], v170 offset:0xa00
	v_max_f32_e32 v121, v49, v49
	v_max_f32_e32 v134, v48, v48
	v_max_f32_e32 v121, v134, v121
	v_max3_f32 v121, v121, v50, v51
	v_max3_f32 v121, v121, v52, v53
	v_max3_f32 v121, v121, v54, v55
	v_max3_f32 v121, v121, v56, v57
	v_max3_f32 v121, v121, v58, v59
	v_max3_f32 v121, v121, v60, v61
	v_max3_f32 v121, v121, v62, v63
	v_max3_f32 v121, v121, v32, v33
	v_max3_f32 v121, v121, v34, v35
	s_waitcnt lgkmcnt(6)
	v_mfma_f32_32x32x16_bf16 v[0:15], v[122:125], v[196:199], v[0:15]
	ds_read_b64_tr_b16 v[196:197], v170 offset:0x1200
	ds_read_b64_tr_b16 v[198:199], v170 offset:0x1a00
	v_max3_f32 v121, v121, v36, v37
	v_max3_f32 v121, v121, v38, v39
	v_max3_f32 v121, v121, v40, v41
	v_max3_f32 v121, v121, v42, v43
	v_max3_f32 v121, v121, v44, v45
	v_max3_f32 v121, v121, v46, v47
	v_mov_b32_e32 v134, v121
	s_nop 1
	v_permlane32_swap_b32_e32 v121, v134
	v_max_f32_e32 v134, v134, v134
	v_max_f32_e32 v121, v121, v121
	v_max_f32_e32 v121, v121, v134
	s_waitcnt lgkmcnt(6)
	v_mfma_f32_32x32x16_bf16 v[0:15], v[126:129], v[200:203], v[0:15]
	ds_read_b64_tr_b16 v[200:201], v170 offset:0x2200
	ds_read_b64_tr_b16 v[202:203], v170 offset:0x2a00
	ds_read_b64_tr_b16 v[208:209], v170 offset:0x3200
	ds_read_b64_tr_b16 v[210:211], v170 offset:0x3a00
	v_max_f32_e32 v252, v120, v120
	v_sub_f32_e32 v135, v121, v120
	v_max_f32_e32 v121, v252, v121
	v_sub_f32_e32 v252, v120, v121
	v_mul_f32_e32 v252, 0x3e16c740, v252
	v_exp_f32_e32 v252, v252
	v_cmp_ge_f32_e32 vcc, s46, v135
	s_cmp_eq_u64 vcc, exec
	s_cselect_b64 s[6:7], -1, 0
	v_cndmask_b32_e64 v253, v121, v120, s[6:7]
	v_mul_f32_e32 v251, 0xbe16c740, v253
	s_waitcnt lgkmcnt(8)
	v_mfma_f32_32x32x16_bf16 v[0:15], v[184:187], v[204:207], v[0:15]
	v_fmamk_f32 v48, v48, 0x3e16c740, v251
	v_fmamk_f32 v49, v49, 0x3e16c740, v251
	v_fmamk_f32 v50, v50, 0x3e16c740, v251
	v_fmamk_f32 v51, v51, 0x3e16c740, v251
	v_fmamk_f32 v52, v52, 0x3e16c740, v251
	v_fmamk_f32 v53, v53, 0x3e16c740, v251
	v_fmamk_f32 v54, v54, 0x3e16c740, v251
	v_fmamk_f32 v55, v55, 0x3e16c740, v251
	v_fmamk_f32 v56, v56, 0x3e16c740, v251
	v_fmamk_f32 v57, v57, 0x3e16c740, v251
	v_fmamk_f32 v58, v58, 0x3e16c740, v251
	v_fmamk_f32 v59, v59, 0x3e16c740, v251
	s_waitcnt lgkmcnt(6)
	v_mfma_f32_32x32x16_bf16 v[16:31], v[130:133], v[192:195], v[16:31]
	v_fmamk_f32 v60, v60, 0x3e16c740, v251
	v_fmamk_f32 v61, v61, 0x3e16c740, v251
	v_fmamk_f32 v62, v62, 0x3e16c740, v251
	v_fmamk_f32 v63, v63, 0x3e16c740, v251
	v_exp_f32_e32 v120, v48
	v_exp_f32_e32 v135, v49
	v_exp_f32_e32 v121, v50
	v_exp_f32_e32 v134, v51
	v_exp_f32_e32 v133, v53
	v_exp_f32_e32 v132, v55
	s_waitcnt lgkmcnt(4)
	v_mfma_f32_32x32x16_bf16 v[16:31], v[122:125], v[196:199], v[16:31]
	v_exp_f32_e32 v131, v57
	v_exp_f32_e32 v130, v59
	v_exp_f32_e32 v122, v52
	v_exp_f32_e32 v123, v54
	v_exp_f32_e32 v124, v56
	v_exp_f32_e32 v125, v58
	s_waitcnt lgkmcnt(2)
	v_mfma_f32_32x32x16_bf16 v[16:31], v[126:129], v[200:203], v[16:31]
	v_exp_f32_e32 v126, v60
	v_exp_f32_e32 v129, v61
	v_exp_f32_e32 v127, v62
	v_exp_f32_e32 v128, v63
	s_waitcnt lgkmcnt(0)
	v_mfma_f32_32x32x16_bf16 v[16:31], v[184:187], v[208:211], v[16:31]
	s_barrier
	s_waitcnt vmcnt(4)
	v_cndmask_b32_e64 v184, v252, 1.0, s[6:7]
	v_cmp_gt_f32_e32 vcc, 1.0, v184
	s_waitcnt vmcnt(4)
	ds_write_b128 v173, v[96:99]
	ds_write_b128 v174, v[100:103]
	s_cbranch_vccz .LBB0_1492
	s_and_saveexec_b64 s[10:11], s[4:5]
	ds_write_b32 v167, v184 offset:128
	s_or_b64 exec, exec, s[10:11]
	s_waitcnt lgkmcnt(0)
	v_add_u32_e32 v208, v149, v146
	ds_read_b128 v[192:195], v208 offset:224
	ds_read_b128 v[196:199], v208 offset:192
	ds_read_b128 v[200:203], v208 offset:160
	ds_read_b128 v[204:207], v208 offset:128
	s_waitcnt lgkmcnt(3)
	v_pk_mul_f32 v[12:13], v[12:13], v[192:193]
	s_waitcnt lgkmcnt(2)
	v_pk_mul_f32 v[8:9], v[8:9], v[196:197]
	s_waitcnt lgkmcnt(1)
	v_pk_mul_f32 v[4:5], v[4:5], v[200:201]
	v_pk_mul_f32 v[14:15], v[14:15], v[194:195]
	v_pk_mul_f32 v[10:11], v[10:11], v[198:199]
	v_pk_mul_f32 v[6:7], v[6:7], v[202:203]
	s_waitcnt lgkmcnt(0)
	v_pk_mul_f32 v[2:3], v[2:3], v[206:207]
	v_pk_mul_f32 v[0:1], v[0:1], v[204:205]
	v_pk_mul_f32 v[28:29], v[28:29], v[192:193]
	v_pk_mul_f32 v[24:25], v[24:25], v[196:197]
	v_pk_mul_f32 v[20:21], v[20:21], v[200:201]
	v_pk_mul_f32 v[30:31], v[30:31], v[194:195]
	v_pk_mul_f32 v[26:27], v[26:27], v[198:199]
	v_pk_mul_f32 v[22:23], v[22:23], v[202:203]
	v_pk_mul_f32 v[18:19], v[18:19], v[206:207]
	v_pk_mul_f32 v[16:17], v[16:17], v[204:205]
